# P2: barrier after step 4 removed (step 0 touches only Gs/Bs/Fs); attention: barrier before the task epilogue removed (on top of v96)
# baseline (speedup 1.0000x reference)
.LBB0_334:
	s_nop 3
	v_lshlrev_b32_e32 v0, 8, v44
	v_mov_b32_e32 v1, v132
	v_lshl_add_u64 v[0:1], v[40:41], 0, v[0:1]
	v_lshl_add_u64 v[2:3], v[42:43], 0, 64
	v_cndmask_b32_e64 v1, v1, v3, s[0:1]
	v_cndmask_b32_e64 v0, v0, v2, s[0:1]
	v_cvt_pk_bf16_f32 v2, v228, v229
	v_cvt_pk_bf16_f32 v3, v230, v231
	global_store_dwordx2 v[0:1], v[2:3], off
	v_cvt_pk_bf16_f32 v2, v232, v233
	v_cvt_pk_bf16_f32 v3, v234, v235
	global_store_dwordx2 v[0:1], v[2:3], off offset:16
	v_cvt_pk_bf16_f32 v2, v236, v237
	v_cvt_pk_bf16_f32 v3, v238, v239
	global_store_dwordx2 v[0:1], v[2:3], off offset:32
	v_cvt_pk_bf16_f32 v2, v240, v241
	v_cvt_pk_bf16_f32 v3, v242, v243
	s_andn2_b64 vcc, exec, s[48:49]
	global_store_dwordx2 v[0:1], v[2:3], off offset:48
	s_waitcnt lgkmcnt(0)
	s_cbranch_vccz .LBB0_437

.LBB0_617:
	v_mov_b32_e32 v64, v167
	s_nop 1
	v_permlane32_swap_b32_e32 v167, v64
	v_add_f32_e32 v78, v167, v64
	v_lshlrev_b64 v[64:65], 12, v[156:157]
	v_lshl_add_u64 v[76:77], s[26:27], 0, v[64:65]
	v_or_b32_e32 v64, s3, v186
	v_rcp_f32_e32 v78, v78
	v_mul_lo_u32 v64, v64, s66
	v_add3_u32 v64, s67, v64, v163
	ds_read2_b64 v[80:83], v64 offset1:2
	ds_read2_b64 v[84:87], v64 offset0:4 offset1:6
	ds_read2_b64 v[88:91], v64 offset0:8 offset1:10
	ds_read2_b64 v[92:95], v64 offset0:12 offset1:14
	ds_read2_b64 v[96:99], v64 offset0:16 offset1:18
	ds_read2_b64 v[72:75], v64 offset0:20 offset1:22
	ds_read2_b64 v[68:71], v64 offset0:24 offset1:26
	ds_read2_b64 v[64:67], v64 offset0:28 offset1:30
	s_mov_b32 s15, s13
	v_pk_mul_f32 v[48:49], v[48:49], v[78:79] op_sel_hi:[1,0]
	s_waitcnt lgkmcnt(7)
	v_lshlrev_b32_e32 v100, 16, v80
	v_and_b32_e32 v101, 0xffff0000, v80
	v_pk_mul_f32 v[50:51], v[50:51], v[78:79] op_sel_hi:[1,0]
	v_lshlrev_b32_e32 v80, 16, v81
	v_and_b32_e32 v81, 0xffff0000, v81
	v_lshl_add_u64 v[76:77], v[76:77], 0, s[14:15]
	v_lshlrev_b32_e32 v128, 1, v159
	v_pk_mul_f32 v[48:49], v[48:49], v[100:101]
	v_pk_mul_f32 v[50:51], v[50:51], v[80:81]
	v_lshl_add_u64 v[76:77], v[76:77], 0, v[128:129]
	v_cvt_pk_bf16_f32 v48, v48, v49
	v_cvt_pk_bf16_f32 v49, v50, v51
	global_store_dwordx2 v[76:77], v[48:49], off offset:2048
	v_pk_mul_f32 v[48:49], v[52:53], v[78:79] op_sel_hi:[1,0]
	v_lshlrev_b32_e32 v50, 16, v82
	v_and_b32_e32 v51, 0xffff0000, v82
	v_pk_mul_f32 v[48:49], v[48:49], v[50:51]
	v_pk_mul_f32 v[50:51], v[54:55], v[78:79] op_sel_hi:[1,0]
	v_lshlrev_b32_e32 v52, 16, v83
	v_and_b32_e32 v53, 0xffff0000, v83
	v_pk_mul_f32 v[50:51], v[50:51], v[52:53]
	v_cvt_pk_bf16_f32 v48, v48, v49
	v_cvt_pk_bf16_f32 v49, v50, v51
	global_store_dwordx2 v[76:77], v[48:49], off offset:2064
	v_pk_mul_f32 v[48:49], v[56:57], v[78:79] op_sel_hi:[1,0]
	s_waitcnt lgkmcnt(6)
	v_lshlrev_b32_e32 v50, 16, v84
	v_and_b32_e32 v51, 0xffff0000, v84
	v_pk_mul_f32 v[48:49], v[48:49], v[50:51]
	v_pk_mul_f32 v[50:51], v[58:59], v[78:79] op_sel_hi:[1,0]
	v_lshlrev_b32_e32 v52, 16, v85
	v_and_b32_e32 v53, 0xffff0000, v85
	v_pk_mul_f32 v[50:51], v[50:51], v[52:53]
	v_cvt_pk_bf16_f32 v48, v48, v49
	v_cvt_pk_bf16_f32 v49, v50, v51
	global_store_dwordx2 v[76:77], v[48:49], off offset:2080
	v_pk_mul_f32 v[48:49], v[60:61], v[78:79] op_sel_hi:[1,0]
	v_lshlrev_b32_e32 v50, 16, v86
	v_and_b32_e32 v51, 0xffff0000, v86
	v_pk_mul_f32 v[48:49], v[48:49], v[50:51]
	v_pk_mul_f32 v[50:51], v[62:63], v[78:79] op_sel_hi:[1,0]
	v_lshlrev_b32_e32 v52, 16, v87
	v_and_b32_e32 v53, 0xffff0000, v87
	v_pk_mul_f32 v[50:51], v[50:51], v[52:53]
	v_cvt_pk_bf16_f32 v48, v48, v49
	v_cvt_pk_bf16_f32 v49, v50, v51
	global_store_dwordx2 v[76:77], v[48:49], off offset:2096
	v_pk_mul_f32 v[32:33], v[32:33], v[78:79] op_sel_hi:[1,0]
	s_waitcnt lgkmcnt(5)
	v_lshlrev_b32_e32 v48, 16, v88
	v_and_b32_e32 v49, 0xffff0000, v88
	v_pk_mul_f32 v[32:33], v[32:33], v[48:49]
	v_pk_mul_f32 v[34:35], v[34:35], v[78:79] op_sel_hi:[1,0]
	v_lshlrev_b32_e32 v48, 16, v89
	v_and_b32_e32 v49, 0xffff0000, v89
	v_pk_mul_f32 v[34:35], v[34:35], v[48:49]
	v_cvt_pk_bf16_f32 v32, v32, v33
	v_cvt_pk_bf16_f32 v33, v34, v35
	global_store_dwordx2 v[76:77], v[32:33], off offset:2112
	v_pk_mul_f32 v[32:33], v[36:37], v[78:79] op_sel_hi:[1,0]
	v_lshlrev_b32_e32 v34, 16, v90
	v_and_b32_e32 v35, 0xffff0000, v90
	v_pk_mul_f32 v[32:33], v[32:33], v[34:35]
	v_pk_mul_f32 v[34:35], v[38:39], v[78:79] op_sel_hi:[1,0]
	v_lshlrev_b32_e32 v36, 16, v91
	v_and_b32_e32 v37, 0xffff0000, v91
	v_pk_mul_f32 v[34:35], v[34:35], v[36:37]
	v_cvt_pk_bf16_f32 v32, v32, v33
	v_cvt_pk_bf16_f32 v33, v34, v35
	global_store_dwordx2 v[76:77], v[32:33], off offset:2128
	v_pk_mul_f32 v[32:33], v[40:41], v[78:79] op_sel_hi:[1,0]
	s_waitcnt lgkmcnt(4)
	v_lshlrev_b32_e32 v34, 16, v92
	v_and_b32_e32 v35, 0xffff0000, v92
	v_pk_mul_f32 v[32:33], v[32:33], v[34:35]
	v_pk_mul_f32 v[34:35], v[42:43], v[78:79] op_sel_hi:[1,0]
	v_lshlrev_b32_e32 v36, 16, v93
	v_and_b32_e32 v37, 0xffff0000, v93
	v_pk_mul_f32 v[34:35], v[34:35], v[36:37]
	v_cvt_pk_bf16_f32 v32, v32, v33
	v_cvt_pk_bf16_f32 v33, v34, v35
	global_store_dwordx2 v[76:77], v[32:33], off offset:2144
	v_pk_mul_f32 v[32:33], v[44:45], v[78:79] op_sel_hi:[1,0]
	v_lshlrev_b32_e32 v34, 16, v94
	v_and_b32_e32 v35, 0xffff0000, v94
	v_pk_mul_f32 v[32:33], v[32:33], v[34:35]
	v_pk_mul_f32 v[34:35], v[46:47], v[78:79] op_sel_hi:[1,0]
	v_lshlrev_b32_e32 v36, 16, v95
	v_and_b32_e32 v37, 0xffff0000, v95
	v_pk_mul_f32 v[34:35], v[34:35], v[36:37]
	v_cvt_pk_bf16_f32 v32, v32, v33
	v_cvt_pk_bf16_f32 v33, v34, v35
	global_store_dwordx2 v[76:77], v[32:33], off offset:2160
	v_pk_mul_f32 v[16:17], v[16:17], v[78:79] op_sel_hi:[1,0]
	s_waitcnt lgkmcnt(3)
	v_lshlrev_b32_e32 v32, 16, v96
	v_and_b32_e32 v33, 0xffff0000, v96
	v_pk_mul_f32 v[16:17], v[16:17], v[32:33]
	v_pk_mul_f32 v[18:19], v[18:19], v[78:79] op_sel_hi:[1,0]
	v_lshlrev_b32_e32 v32, 16, v97
	v_and_b32_e32 v33, 0xffff0000, v97
	v_pk_mul_f32 v[18:19], v[18:19], v[32:33]
	v_cvt_pk_bf16_f32 v16, v16, v17
	v_cvt_pk_bf16_f32 v17, v18, v19
	global_store_dwordx2 v[76:77], v[16:17], off offset:2176
	v_pk_mul_f32 v[16:17], v[20:21], v[78:79] op_sel_hi:[1,0]
	v_lshlrev_b32_e32 v18, 16, v98
	v_and_b32_e32 v19, 0xffff0000, v98
	v_pk_mul_f32 v[16:17], v[16:17], v[18:19]
	v_pk_mul_f32 v[18:19], v[22:23], v[78:79] op_sel_hi:[1,0]
	v_lshlrev_b32_e32 v20, 16, v99
	v_and_b32_e32 v21, 0xffff0000, v99
	v_pk_mul_f32 v[18:19], v[18:19], v[20:21]
	v_cvt_pk_bf16_f32 v16, v16, v17
	v_cvt_pk_bf16_f32 v17, v18, v19
	global_store_dwordx2 v[76:77], v[16:17], off offset:2192
	v_pk_mul_f32 v[16:17], v[24:25], v[78:79] op_sel_hi:[1,0]
	s_waitcnt lgkmcnt(2)
	v_lshlrev_b32_e32 v18, 16, v72
	v_and_b32_e32 v19, 0xffff0000, v72
	v_pk_mul_f32 v[16:17], v[16:17], v[18:19]
	v_pk_mul_f32 v[18:19], v[26:27], v[78:79] op_sel_hi:[1,0]
	v_lshlrev_b32_e32 v20, 16, v73
	v_and_b32_e32 v21, 0xffff0000, v73
	v_pk_mul_f32 v[18:19], v[18:19], v[20:21]
	v_cvt_pk_bf16_f32 v16, v16, v17
	v_cvt_pk_bf16_f32 v17, v18, v19
	global_store_dwordx2 v[76:77], v[16:17], off offset:2208
	v_pk_mul_f32 v[16:17], v[28:29], v[78:79] op_sel_hi:[1,0]
	v_lshlrev_b32_e32 v18, 16, v74
	v_and_b32_e32 v19, 0xffff0000, v74
	v_pk_mul_f32 v[16:17], v[16:17], v[18:19]
	v_pk_mul_f32 v[18:19], v[30:31], v[78:79] op_sel_hi:[1,0]
	v_lshlrev_b32_e32 v20, 16, v75
	v_and_b32_e32 v21, 0xffff0000, v75
	v_pk_mul_f32 v[18:19], v[18:19], v[20:21]
	v_cvt_pk_bf16_f32 v16, v16, v17
	v_cvt_pk_bf16_f32 v17, v18, v19
	global_store_dwordx2 v[76:77], v[16:17], off offset:2224
	v_pk_mul_f32 v[0:1], v[0:1], v[78:79] op_sel_hi:[1,0]
	s_waitcnt lgkmcnt(1)
	v_lshlrev_b32_e32 v16, 16, v68
	v_and_b32_e32 v17, 0xffff0000, v68
	v_pk_mul_f32 v[0:1], v[0:1], v[16:17]
	v_pk_mul_f32 v[2:3], v[2:3], v[78:79] op_sel_hi:[1,0]
	v_lshlrev_b32_e32 v16, 16, v69
	v_and_b32_e32 v17, 0xffff0000, v69
	v_pk_mul_f32 v[2:3], v[2:3], v[16:17]
	v_cvt_pk_bf16_f32 v0, v0, v1
	v_cvt_pk_bf16_f32 v1, v2, v3
	global_store_dwordx2 v[76:77], v[0:1], off offset:2240
	v_pk_mul_f32 v[0:1], v[4:5], v[78:79] op_sel_hi:[1,0]
	v_lshlrev_b32_e32 v2, 16, v70
	v_and_b32_e32 v3, 0xffff0000, v70
	v_pk_mul_f32 v[0:1], v[0:1], v[2:3]
	v_pk_mul_f32 v[2:3], v[6:7], v[78:79] op_sel_hi:[1,0]
	v_lshlrev_b32_e32 v4, 16, v71
	v_and_b32_e32 v5, 0xffff0000, v71
	v_pk_mul_f32 v[2:3], v[2:3], v[4:5]
	v_cvt_pk_bf16_f32 v0, v0, v1
	v_cvt_pk_bf16_f32 v1, v2, v3
	global_store_dwordx2 v[76:77], v[0:1], off offset:2256
	v_pk_mul_f32 v[0:1], v[8:9], v[78:79] op_sel_hi:[1,0]
	s_waitcnt lgkmcnt(0)
	v_lshlrev_b32_e32 v2, 16, v64
	v_and_b32_e32 v3, 0xffff0000, v64
	v_pk_mul_f32 v[0:1], v[0:1], v[2:3]
	v_pk_mul_f32 v[2:3], v[10:11], v[78:79] op_sel_hi:[1,0]
	v_lshlrev_b32_e32 v4, 16, v65
	v_and_b32_e32 v5, 0xffff0000, v65
	v_pk_mul_f32 v[2:3], v[2:3], v[4:5]
	v_cvt_pk_bf16_f32 v0, v0, v1
	v_cvt_pk_bf16_f32 v1, v2, v3
	global_store_dwordx2 v[76:77], v[0:1], off offset:2272
	v_pk_mul_f32 v[0:1], v[12:13], v[78:79] op_sel_hi:[1,0]
	v_lshlrev_b32_e32 v2, 16, v66
	v_and_b32_e32 v3, 0xffff0000, v66
	v_pk_mul_f32 v[0:1], v[0:1], v[2:3]
	v_pk_mul_f32 v[2:3], v[14:15], v[78:79] op_sel_hi:[1,0]
	v_lshlrev_b32_e32 v4, 16, v67
	v_and_b32_e32 v5, 0xffff0000, v67
	v_pk_mul_f32 v[2:3], v[2:3], v[4:5]
	v_cvt_pk_bf16_f32 v0, v0, v1
	v_cvt_pk_bf16_f32 v1, v2, v3
	global_store_dwordx2 v[76:77], v[0:1], off offset:2288
